# split-K tail of N=1024 GEMMs: all K-range workgroups wait for the slabs and share the final row reduction instead of the last arriver alone; padding-row partial sums not stored
# speedup vs baseline: 1.0531x; 1.0531x over previous
;     __device__ __forceinline__ void operator()(const f32x4 (&acc)[2][2][4][2], const Unit& u, int wr, int wc, int fr, int fq) const {
;     ...
;         if (SLAB && u.pm == 64) {
;             float* sp = SLAB + ((size_t)(u.kt0 / u.nt) * 256 + wr * 64 + fr) * 1024 + col0;
; #pragma unroll
;             for (int ai = 0; ai < 2; ++ai)
; #pragma unroll
;                 for (int m = 0; m < 4; ++m)
; #pragma unroll
;                     for (int bj = 0; bj < 2; ++bj) { float* p = sp + (size_t)(ai * HALF + m * 16) * 1024 + bj * HALF; *(f32x4*)p = acc[ai][bj][m][0]; *(f32x4*)(p + 4) = acc[ai][bj][m][1]; }
;             volatile __attribute__((address_space(3))) unsigned* lflag = (volatile __attribute__((address_space(3))) unsigned*)(lds_misc);
;             asm volatile("s_waitcnt vmcnt(0)" ::: "memory"); __syncthreads();
;             if (wr == 0 && wc == 0 && fr == 0 && fq == 0) { __builtin_amdgcn_fence(__ATOMIC_RELEASE, "agent"); asm volatile("s_waitcnt vmcnt(0)" ::: "memory");
;                 lflag[0] = __hip_atomic_fetch_add(CNT + u.pn, 1u, __ATOMIC_RELAXED, __HIP_MEMORY_SCOPE_AGENT); }
.LBB0_382:
	s_and_b64 vcc, exec, s[16:17]
	s_cbranch_vccz .LBB0_474
	s_abs_i32 s3, s87
	v_cvt_f32_u32_e32 v128, s3
	s_sub_i32 s18, 0, s3
	s_abs_i32 s17, s81
	s_xor_b32 s16, s81, s87
	v_rcp_iflag_f32_e32 v128, v128
	s_ashr_i32 s16, s16, 31
	v_mul_f32_e32 v128, 0x4f7ffffe, v128
	v_cvt_u32_f32_e32 v128, v128
	s_nop 0
	v_readfirstlane_b32 s19, v128
	s_mul_i32 s18, s18, s19
	s_mul_hi_u32 s18, s19, s18
	s_add_i32 s19, s19, s18
	s_mul_hi_u32 s18, s17, s19
	s_mul_i32 s19, s18, s3
	s_sub_i32 s17, s17, s19
	s_add_i32 s20, s18, 1
	s_sub_i32 s19, s17, s3
	s_cmp_ge_u32 s17, s3
	s_cselect_b32 s18, s20, s18
	s_cselect_b32 s17, s19, s17
	s_add_i32 s19, s18, 1
	s_cmp_ge_u32 s17, s3
	s_cselect_b32 s3, s19, s18
	s_xor_b32 s3, s3, s16
	s_sub_i32 s16, s3, s16
	s_ashr_i32 s17, s16, 31
	s_lshl_b64 s[16:17], s[16:17], 20
	v_lshl_add_u64 v[128:129], v[188:189], 0, s[16:17]
	v_lshl_add_u64 v[128:129], v[164:165], 2, v[128:129]
	s_mov_b32 s3, 0x10000
	global_store_dwordx4 v[128:129], v[124:127], off
	global_store_dwordx4 v[128:129], v[120:123], off offset:16
	global_store_dwordx4 v[128:129], v[104:107], off offset:512
	global_store_dwordx4 v[128:129], v[96:99], off offset:528
	s_nop 1
	v_add_co_u32_e32 v96, vcc, s3, v128
	s_mov_b32 s3, 0x20000
	s_nop 0
	v_addc_co_u32_e32 v97, vcc, 0, v129, vcc
	global_store_dwordx4 v[96:97], v[116:119], off
	global_store_dwordx4 v[96:97], v[112:115], off offset:16
	global_store_dwordx4 v[96:97], v[88:91], off offset:512
	global_store_dwordx4 v[96:97], v[80:83], off offset:528
	s_nop 1
	v_add_co_u32_e32 v80, vcc, s3, v128
	s_mov_b32 s3, 0x30000
	s_nop 0
	v_addc_co_u32_e32 v81, vcc, 0, v129, vcc
	global_store_dwordx4 v[80:81], v[108:111], off
	global_store_dwordx4 v[80:81], v[100:103], off offset:16
	global_store_dwordx4 v[80:81], v[76:79], off offset:512
	global_store_dwordx4 v[80:81], v[72:75], off offset:528
	s_nop 1
	v_add_co_u32_e32 v72, vcc, s3, v128
	s_mov_b32 s3, 0x80000
	s_nop 0
	v_addc_co_u32_e32 v73, vcc, 0, v129, vcc
	global_store_dwordx4 v[72:73], v[92:95], off
	global_store_dwordx4 v[72:73], v[84:87], off offset:16
	global_store_dwordx4 v[72:73], v[68:71], off offset:512
	global_store_dwordx4 v[72:73], v[64:67], off offset:528
	s_nop 1
	v_add_co_u32_e32 v64, vcc, s3, v128
	s_mov_b32 s3, 0x90000
	s_nop 0
	v_addc_co_u32_e32 v65, vcc, 0, v129, vcc
	s_nop 1
	v_add_co_u32_e32 v36, vcc, s3, v128
	s_mov_b32 s3, 0xa0000
	s_nop 0
	v_addc_co_u32_e32 v37, vcc, 0, v129, vcc
	s_nop 1
	v_add_co_u32_e32 v20, vcc, s3, v128
	s_nop 1
	v_addc_co_u32_e32 v21, vcc, 0, v129, vcc
	s_nop 1
	v_add_co_u32_e32 v8, vcc, 0xb0000, v128
	s_nop 1
	v_addc_co_u32_e32 v9, vcc, 0, v129, vcc
	s_waitcnt vmcnt(0)
	s_waitcnt vmcnt(0)
	s_barrier
	s_and_saveexec_b64 s[16:17], s[8:9]
	s_cbranch_execz .LBB0_387
	s_mov_b64 s[18:19], exec
	buffer_wbl2 sc1
	s_waitcnt vmcnt(0)
	v_mbcnt_lo_u32_b32 v0, s18, 0
	v_mbcnt_hi_u32_b32 v0, s19, v0
	v_cmp_eq_u32_e32 vcc, 0, v0
	s_and_saveexec_b64 s[20:21], vcc
	s_cbranch_execz .LBB0_386
	s_ashr_i32 s59, s58, 31
	s_lshl_b64 s[62:63], s[58:59], 2
	v_readlane_b32 s3, v248, 12
	s_add_u32 s62, s3, s62
	v_readlane_b32 s3, v248, 16
	s_addc_u32 s63, s3, s63
	s_bcnt1_i32_b64 s3, s[18:19]
	v_mov_b32_e32 v1, s3
	global_atomic_add v1, v211, v1, s[62:63] sc0

;     __device__ __forceinline__ void operator()(const f32x4 (&acc)[2][2][4][2], const Unit& u, int wr, int wc, int fr, int fq) const {
;     ...
;             if (wr == 0 && wc == 0 && fr == 0 && fq == 0) { __builtin_amdgcn_fence(__ATOMIC_RELEASE, "agent"); asm volatile("s_waitcnt vmcnt(0)" ::: "memory");
;                 lflag[0] = __hip_atomic_fetch_add(CNT + u.pn, 1u, __ATOMIC_RELAXED, __HIP_MEMORY_SCOPE_AGENT); }
;             __syncthreads();
;             const bool last = (lflag[0] == (unsigned)(nsplit - 1));
;             if (last) {
;                 __builtin_amdgcn_fence(__ATOMIC_ACQUIRE, "agent"); asm volatile("s_waitcnt vmcnt(0)" ::: "memory");
;                 const int lane = fq * 16 + fr, wv = wr * 4 + wc;
;                 constexpr int RB = 4;
;                 for (int r0 = wv * 16; r0 < wv * 16 + 16; r0 += RB) {
.Lmy_tail_spin:
	global_load_dword v2, v211, s[62:63] sc1
	s_waitcnt vmcnt(0)
	v_cmp_lt_u32_e32 vcc, s49, v2
	s_cbranch_vccnz .Lmy_tail_spun
	s_sleep 1
	s_branch .Lmy_tail_spin
.Lmy_tail_spun:
	v_readfirstlane_b32 s3, v1
	s_nop 1
	v_add_u32_e32 v0, s3, v0
	v_readlane_b32 s3, v249, 23
	s_nop 1
	v_mov_b32_e32 v1, s3
	ds_write_b32 v1, v0
.LBB0_387:
	s_or_b64 exec, exec, s[16:17]
	v_readlane_b32 s3, v249, 23
	s_waitcnt lgkmcnt(0)
	s_barrier
	v_mov_b32_e32 v0, s3
	ds_read_b32 v0, v0
	s_waitcnt lgkmcnt(0)
	v_readfirstlane_b32 s100, v0
	s_add_i32 s101, s49, 1
	s_add_i32 s16, s35, 4
	s_lshr_b32 s16, s16, 2
	s_nop 3
.Lmy_tail_adv:
	s_cmp_ge_u32 s100, s16
	s_cbranch_scc1 .Lmy_tail_adv_done
	s_add_i32 s100, s100, s101
	s_branch .Lmy_tail_adv
.Lmy_tail_adv_done:
	buffer_inv sc1
	s_waitcnt vmcnt(0)
	s_lshl_b32 s16, s58, 2
	s_ashr_i32 s81, s80, 31
	s_ashr_i32 s17, s16, 31
	v_lshl_add_u64 v[200:201], s[80:81], 2, v[194:195]
	v_lshl_add_u64 v[202:203], s[16:17], 2, v[196:197]
	v_lshl_add_u64 v[204:205], s[80:81], 1, v[198:199]
	s_mov_b32 s3, s35
	s_branch .LBB0_390

;     __device__ __forceinline__ void operator()(const f32x4 (&acc)[2][2][4][2], const Unit& u, int wr, int wc, int fr, int fq) const {
;     ...
;                 for (int r0 = wv * 16; r0 < wv * 16 + 16; r0 += RB) {
;                     f32x4 a[RB]; unsigned long long hw[RB];
; #pragma unroll
;                     for (int q = 0; q < RB; ++q) {
;                         f32x4 sl[11];
; #pragma unroll
;                         for (int s = 0; s < 11; ++s) sl[s] = s < nsplit ? *((const f32x4*)(SLAB + ((size_t)s * 256 + r0 + q) * 1024 + u.pn * BM) + lane) : (f32x4){0.f, 0.f, 0.f, 0.f};
;                         hw[q] = *(const unsigned long long*)(HB + (size_t)(64 * 256 + r0 + q) * 1024 + u.pn * BM + 4 * lane);
.LBB0_390:
	s_add_i32 s16, s3, 4
	s_lshr_b32 s16, s16, 2
	s_cmp_lg_u32 s16, s100
	s_cbranch_scc1 .LBB0_389
	s_add_i32 s100, s100, s101
	v_add_co_u32_e32 v0, vcc, 0x100000, v200
	v_mov_b32_e32 v92, 0
	s_nop 0
	v_addc_co_u32_e32 v1, vcc, 0, v201, vcc
	v_add_co_u32_e32 v2, vcc, 0x200000, v200
	v_mov_b32_e32 v108, 0
	s_nop 0
	v_addc_co_u32_e32 v3, vcc, 0, v201, vcc
	global_load_dwordx4 v[64:67], v[0:1], off
	global_load_dwordx4 v[68:71], v[2:3], off
	v_add_co_u32_e32 v0, vcc, 0x300000, v200
	v_mov_b32_e32 v109, 0
	s_nop 0
	v_addc_co_u32_e32 v1, vcc, 0, v201, vcc
	global_load_dwordx4 v[84:87], v[200:201], off
	global_load_dwordx4 v[80:83], v[0:1], off
	v_cndmask_b32_e64 v0, 0, 1, s[26:27]
	v_cmp_ne_u32_e64 s[16:17], 1, v0
	s_andn2_b64 vcc, exec, s[26:27]
	v_mov_b32_e32 v110, 0
	v_mov_b32_e32 v111, 0
	s_cbranch_vccnz .LBB0_392
	v_add_co_u32_e32 v0, vcc, 0x400000, v200
	s_nop 1
	v_addc_co_u32_e32 v1, vcc, 0, v201, vcc
	global_load_dwordx4 v[108:111], v[0:1], off

; #define LAS __attribute__((address_space(3)))
; __global__ void __launch_bounds__(NTHR, 2) fwd_megakernel(Args args) {
;     extern __shared__ __attribute__((aligned(16))) unsigned char lds_raw[];
;     LAS unsigned char* lds = (LAS unsigned char*)lds_raw;
	.amdhsa_kernel _Z14fwd_megakernel4Args
		.amdhsa_group_segment_fixed_size 0
		.amdhsa_private_segment_fixed_size 0
		.amdhsa_kernarg_size 416
		.amdhsa_user_sgpr_count 2
		.amdhsa_user_sgpr_dispatch_ptr 0
		.amdhsa_user_sgpr_queue_ptr 0
		.amdhsa_user_sgpr_kernarg_segment_ptr 1
		.amdhsa_user_sgpr_dispatch_id 0
		.amdhsa_user_sgpr_kernarg_preload_length 0
		.amdhsa_user_sgpr_kernarg_preload_offset 0
		.amdhsa_user_sgpr_private_segment_size 0
		.amdhsa_uses_dynamic_stack 0
		.amdhsa_enable_private_segment 0
		.amdhsa_system_sgpr_workgroup_id_x 1
		.amdhsa_system_sgpr_workgroup_id_y 0
		.amdhsa_system_sgpr_workgroup_id_z 0
		.amdhsa_system_sgpr_workgroup_info 0
		.amdhsa_system_vgpr_workitem_id 2
		.amdhsa_next_free_vgpr 251
		.amdhsa_next_free_sgpr 102
		.amdhsa_accum_offset 252
		.amdhsa_reserve_vcc 1
		.amdhsa_float_round_mode_32 0
		.amdhsa_float_round_mode_16_64 0
		.amdhsa_float_denorm_mode_32 3
		.amdhsa_float_denorm_mode_16_64 3
		.amdhsa_dx10_clamp 1
		.amdhsa_ieee_mode 1
		.amdhsa_fp16_overflow 0
		.amdhsa_tg_split 0
		.amdhsa_exception_fp_ieee_invalid_op 0
		.amdhsa_exception_fp_denorm_src 0
		.amdhsa_exception_fp_ieee_div_zero 0
		.amdhsa_exception_fp_ieee_overflow 0
		.amdhsa_exception_fp_ieee_underflow 0
		.amdhsa_exception_fp_ieee_inexact 0
		.amdhsa_exception_int_div_zero 0
	.end_amdhsa_kernel

; #define LAS __attribute__((address_space(3)))
; __global__ void __launch_bounds__(NTHR, 2) fwd_megakernel(Args args) {
;     extern __shared__ __attribute__((aligned(16))) unsigned char lds_raw[];
;     LAS unsigned char* lds = (LAS unsigned char*)lds_raw;
amdhsa.kernels:
  - .agpr_count:     0
    .args:
      - .offset:         0
        .size:           160
        .value_kind:     by_value
      - .offset:         160
        .size:           4
        .value_kind:     hidden_block_count_x
      - .offset:         164
        .size:           4
        .value_kind:     hidden_block_count_y
      - .offset:         168
        .size:           4
        .value_kind:     hidden_block_count_z
      - .offset:         172
        .size:           2
        .value_kind:     hidden_group_size_x
      - .offset:         174
        .size:           2
        .value_kind:     hidden_group_size_y
      - .offset:         176
        .size:           2
        .value_kind:     hidden_group_size_z
      - .offset:         178
        .size:           2
        .value_kind:     hidden_remainder_x
      - .offset:         180
        .size:           2
        .value_kind:     hidden_remainder_y
      - .offset:         182
        .size:           2
        .value_kind:     hidden_remainder_z
      - .offset:         200
        .size:           8
        .value_kind:     hidden_global_offset_x
      - .offset:         208
        .size:           8
        .value_kind:     hidden_global_offset_y
      - .offset:         216
        .size:           8
        .value_kind:     hidden_global_offset_z
      - .offset:         224
        .size:           2
        .value_kind:     hidden_grid_dims
      - .offset:         248
        .size:           8
        .value_kind:     hidden_multigrid_sync_arg
      - .offset:         280
        .size:           4
        .value_kind:     hidden_dynamic_lds_size
    .group_segment_fixed_size: 0
    .kernarg_segment_align: 8
    .kernarg_segment_size: 416
    .language:       OpenCL C
    .language_version:
      - 2
      - 0
    .max_flat_workgroup_size: 512
    .name:           _Z14fwd_megakernel4Args
    .private_segment_fixed_size: 0
    .sgpr_count:     108
    .sgpr_spill_count: 158
    .symbol:         _Z14fwd_megakernel4Args.kd
    .uniform_work_group_size: 1
    .uses_dynamic_stack: false
    .vgpr_count:     251
    .vgpr_spill_count: 0
    .wavefront_size: 64
